# P1 MFMA issue order: every consecutive MFMA pair either chains the accumulator (same D, k0->k1 / k1->k0) or shares a source operand (snake over the 8 accumulator quads of a block)
# speedup vs baseline: 1.0241x; 1.0173x over previous
; #define PG8_LAS __attribute__((address_space(3)))
; #define PG8_STAGE(bufoff, gbase, voff) do { _Pragma("unroll") for (int _i = 0; _i < 2; ++_i) \
;         __builtin_amdgcn_global_load_lds((const unsigned*)((const char*)(gbase) + (voff)[_i]), (PG8_LAS unsigned*)(lds + (bufoff) + ldsw + _i * 8192), 16, 0, 0); } while (0)
; #define PG8_LDA(dst, b, h) do { _Pragma("unroll") for (int m = 0; m < 4; ++m) _Pragma("unroll") for (int k = 0; k < 2; ++k) dst[m][k] = *(const PG8_LAS bf16x8*)(lds + PG8_SA(b, h) + aoff + m * 2048 + k * 1024); } while (0)
; template <class Epi, class Sched, bool ALIGN_EPI = false, bool SP2 = false, bool RS = false, bool BPRE = false>
; __device__ __forceinline__ void gemm_phase(PG8_LAS unsigned char* lds, const Gemm g, const Sched& S, const Epi& E, const float* rs_ss = nullptr, PG8_LAS float* rs_tab = nullptr) {
;     ...
;         const bool has_next = S.next(ui + 1, nxt);
;         const char* nA = has_next ? (const char*)g.A + (size_t)nxt.pm * tstep : cA; const char* nB = has_next ? (const char*)g.Bt + (size_t)nxt.pn * tstep : cB;
;         for (int t = 0; t < nt; t += 2) {
;             const bool last = (t == nt - 2);
;             if constexpr (RS) { if (t == 16 || t == 32) { const PG8_LAS float* tp = rs_tab + (ui & 1) * 768 + (t == 32 ? 256 : 0);
;                 _Pragma("unroll") for (int a = 0; a < 2; ++a) _Pragma("unroll") for (int m = 0; m < 4; ++m) { const float f = tp[a * HALF + wr * 64 + m * 16 + fr];
;                     _Pragma("unroll") for (int b = 0; b < 2; ++b) _Pragma("unroll") for (int n = 0; n < 2; ++n) acc[a][b][m][n] = acc[a][b][m][n] * f; } } }
;             const char* a1 = cA + (size_t)(t + 1) * kstep;
;             const char* a2 = last ? nA : cA + (size_t)(t + 2) * kstep; const char* b2 = last ? nB : cB + (size_t)(t + 2) * kstep;
;             const char* a3 = a2 + kstep; const char* b3 = b2 + kstep;
;             if (last && has_next) S.a_ready(nxt);
;             if constexpr (SP2) {
;             PG8_LDB(B0, 0, 0); PG8_LDB(B1, 0, 1); PG8_SCHED; PG8_LDA(At, 0, 0); PG8_STAGE(PG8_SA(1, 1), a1 + hstep, voffA);
;             PG8_WAIT_V(8); PG8_WAIT_L(0); PG8_BAR; PG8_MMA(0, 0, At, B0); PG8_MMA(0, 1, At, B1); PG8_BAR; PG8_SCHED;
;             PG8_LDA(At, 0, 1); PG8_STAGE(PG8_SB(0, 0), b2, voffB); PG8_STAGE(PG8_SB(0, 1), b2 + hstep, voffB); PG8_STAGE(PG8_SA(0, 0), a2, voffA);
.LBB0_195:
	s_ashr_i32 s19, s18, 31
	s_lshl_b64 s[20:21], s[18:19], 20
	s_add_u32 s20, s30, s20
	s_addc_u32 s21, s31, s21
	s_and_b64 s[44:45], s[6:7], exec
	s_cselect_b32 s5, s21, s57
	s_cselect_b32 s19, s20, s56
	s_ashr_i32 s17, s16, 31
	s_lshl_b64 s[44:45], s[16:17], 20
	s_add_u32 s44, s24, s44
	s_addc_u32 s45, s25, s45
	s_and_b64 s[60:61], s[6:7], exec
	s_cselect_b32 s17, s45, s59
	s_cselect_b32 s47, s44, s58
	s_add_u32 s56, s56, 0x84000
	s_addc_u32 s57, s57, 0
	s_add_u32 s87, s58, 0x8000
	s_addc_u32 s88, s59, 0
	s_mov_b32 s89, -2
	s_waitcnt lgkmcnt(0)
	ds_read_b128 v[130:133], v161
	ds_read_b128 v[134:137], v161 offset:1024
	ds_read_b128 v[152:155], v161 offset:2048
	ds_read_b128 v[156:159], v161 offset:3072
	ds_read_b128 v[166:169], v162
	ds_read_b128 v[170:173], v162 offset:1024
	ds_read_b128 v[174:177], v162 offset:2048
	ds_read_b128 v[182:185], v162 offset:3072
	s_add_u32 s58, s56, 0xfff84000
	s_addc_u32 s59, s57, -1
	s_cmp_eq_u32 s89, 28
	s_cselect_b32 s70, s19, s58
	s_cselect_b32 s71, s5, s59
	s_cselect_b32 s60, s47, s87
	s_cselect_b32 s61, s17, s88
	s_add_u32 s58, s70, 0x4000
	s_addc_u32 s59, s71, 0
	v_lshl_add_u64 v[178:179], s[56:57], 0, v[138:139]
	s_add_i32 m0, s72, 0xc000
	ds_read_b128 v[186:189], v163
	ds_read_b128 v[190:193], v163 offset:1024
	ds_read_b128 v[194:197], v163 offset:2048
	ds_read_b128 v[198:201], v163 offset:3072
	ds_read_b128 v[202:205], v163 offset:4096
	ds_read_b128 v[206:209], v163 offset:5120
	ds_read_b128 v[210:213], v163 offset:6144
	ds_read_b128 v[214:217], v163 offset:7168
	global_load_lds_dwordx4 v[178:179], off
	v_lshl_add_u64 v[178:179], s[56:57], 0, v[146:147]
	s_add_i32 m0, s72, 0xe000
	s_nop 0
	global_load_lds_dwordx4 v[178:179], off
	s_waitcnt vmcnt(8)
	s_waitcnt lgkmcnt(0)
	s_barrier
	s_setprio 1
	s_waitcnt lgkmcnt(0)
	v_mfma_f32_16x16x32_bf16 v[126:129], v[130:133], v[186:189], 0
	v_mfma_f32_16x16x32_bf16 v[126:129], v[134:137], v[190:193], v[126:129]
	v_mfma_f32_16x16x32_bf16 v[122:125], v[156:159], v[190:193], 0
	v_mfma_f32_16x16x32_bf16 v[122:125], v[152:155], v[186:189], v[122:125]
	v_mfma_f32_16x16x32_bf16 v[106:109], v[152:155], v[194:197], 0
	v_mfma_f32_16x16x32_bf16 v[106:109], v[156:159], v[198:201], v[106:109]
	v_mfma_f32_16x16x32_bf16 v[110:113], v[134:137], v[198:201], 0
	v_mfma_f32_16x16x32_bf16 v[110:113], v[130:133], v[194:197], v[110:113]
	v_mfma_f32_16x16x32_bf16 v[94:97], v[130:133], v[202:205], 0
	v_mfma_f32_16x16x32_bf16 v[94:97], v[134:137], v[206:209], v[94:97]
	v_mfma_f32_16x16x32_bf16 v[90:93], v[156:159], v[206:209], 0
	v_mfma_f32_16x16x32_bf16 v[90:93], v[152:155], v[202:205], v[90:93]
	v_mfma_f32_16x16x32_bf16 v[74:77], v[152:155], v[210:213], 0
	v_mfma_f32_16x16x32_bf16 v[74:77], v[156:159], v[214:217], v[74:77]
	v_mfma_f32_16x16x32_bf16 v[78:81], v[134:137], v[214:217], 0
	v_mfma_f32_16x16x32_bf16 v[78:81], v[130:133], v[210:213], v[78:81]
	s_setprio 0
	s_setprio 1
	v_mfma_f32_16x16x32_bf16 v[118:121], v[166:169], v[186:189], 0
	v_mfma_f32_16x16x32_bf16 v[118:121], v[170:173], v[190:193], v[118:121]
	v_mfma_f32_16x16x32_bf16 v[114:117], v[182:185], v[190:193], 0
	v_mfma_f32_16x16x32_bf16 v[114:117], v[174:177], v[186:189], v[114:117]
	v_mfma_f32_16x16x32_bf16 v[98:101], v[174:177], v[194:197], 0
	v_mfma_f32_16x16x32_bf16 v[98:101], v[182:185], v[198:201], v[98:101]
	v_mfma_f32_16x16x32_bf16 v[102:105], v[170:173], v[198:201], 0
	v_mfma_f32_16x16x32_bf16 v[102:105], v[166:169], v[194:197], v[102:105]
	v_mfma_f32_16x16x32_bf16 v[86:89], v[166:169], v[202:205], 0
	v_mfma_f32_16x16x32_bf16 v[86:89], v[170:173], v[206:209], v[86:89]
	v_mfma_f32_16x16x32_bf16 v[82:85], v[182:185], v[206:209], 0
	v_mfma_f32_16x16x32_bf16 v[82:85], v[174:177], v[202:205], v[82:85]
	v_mfma_f32_16x16x32_bf16 v[66:69], v[174:177], v[210:213], 0
	v_mfma_f32_16x16x32_bf16 v[66:69], v[182:185], v[214:217], v[66:69]
	v_mfma_f32_16x16x32_bf16 v[70:73], v[170:173], v[214:217], 0
	v_mfma_f32_16x16x32_bf16 v[70:73], v[166:169], v[210:213], v[70:73]
	s_setprio 0
	s_barrier
	s_add_i32 s90, s83, s15
	v_lshl_add_u64 v[178:179], s[60:61], 0, v[138:139]
	s_mov_b32 m0, s90
	ds_read_b128 v[186:189], v163 offset:16384
	ds_read_b128 v[190:193], v163 offset:17408
	ds_read_b128 v[194:197], v163 offset:18432
	ds_read_b128 v[198:201], v163 offset:19456
	ds_read_b128 v[202:205], v163 offset:20480
	ds_read_b128 v[206:209], v163 offset:21504
	ds_read_b128 v[210:213], v163 offset:22528
	ds_read_b128 v[214:217], v163 offset:23552
	global_load_lds_dwordx4 v[178:179], off
	s_add_i32 m0, s90, 0x2000
	s_add_u32 s90, s60, 0x80000
	v_lshl_add_u64 v[178:179], s[60:61], 0, v[140:141]
	s_addc_u32 s91, s61, 0
	s_add_i32 s92, s86, s15
	global_load_lds_dwordx4 v[178:179], off
	v_lshl_add_u64 v[178:179], s[90:91], 0, v[138:139]
	s_mov_b32 m0, s92
	s_nop 0
	global_load_lds_dwordx4 v[178:179], off
	v_lshl_add_u64 v[178:179], s[90:91], 0, v[140:141]
	s_add_i32 m0, s92, 0x2000
	s_nop 0
	global_load_lds_dwordx4 v[178:179], off
	v_lshl_add_u64 v[178:179], s[70:71], 0, v[138:139]
	s_mov_b32 m0, s72
	s_nop 0
	global_load_lds_dwordx4 v[178:179], off
	v_lshl_add_u64 v[178:179], s[70:71], 0, v[140:141]
	s_mov_b32 m0, s73
	s_nop 0
	global_load_lds_dwordx4 v[178:179], off
	s_waitcnt vmcnt(8)
	s_waitcnt lgkmcnt(0)
	s_barrier
; #define PG8_STAGE(bufoff, gbase, voff) do { _Pragma("unroll") for (int _i = 0; _i < 2; ++_i) \
;         __builtin_amdgcn_global_load_lds((const unsigned*)((const char*)(gbase) + (voff)[_i]), (PG8_LAS unsigned*)(lds + (bufoff) + ldsw + _i * 8192), 16, 0, 0); } while (0)
; #define PG8_LDA(dst, b, h) do { _Pragma("unroll") for (int m = 0; m < 4; ++m) _Pragma("unroll") for (int k = 0; k < 2; ++k) dst[m][k] = *(const PG8_LAS bf16x8*)(lds + PG8_SA(b, h) + aoff + m * 2048 + k * 1024); } while (0)
; #define PG8_LDB(dst, b, h) do { _Pragma("unroll") for (int n = 0; n < 2; ++n) _Pragma("unroll") for (int k = 0; k < 2; ++k) dst[n][k] = *(const PG8_LAS bf16x8*)(lds + PG8_SB(b, h) + boff + n * 2048 + k * 1024); } while (0)
; #define PG8_MMA(ai, bj, At, Bt) do { __builtin_amdgcn_s_setprio(1); _Pragma("unroll") for (int m = 0; m < 4; ++m) _Pragma("unroll") for (int n = 0; n < 2; ++n) _Pragma("unroll") for (int k = 0; k < 2; ++k) \
;         acc[ai][bj][m][n] = __builtin_amdgcn_mfma_f32_16x16x32_bf16(Bt[n][k], At[m][k], acc[ai][bj][m][n], 0, 0, 0); __builtin_amdgcn_s_setprio(0); } while (0)
; #define PG8_WAIT_V(n) asm volatile("s_waitcnt vmcnt(" #n ")" ::: "memory")
; #define PG8_WAIT_L(n) asm volatile("s_waitcnt lgkmcnt(" #n ")" ::: "memory")
; #define PG8_BAR __builtin_amdgcn_s_barrier()
; #define PG8_SCHED __builtin_amdgcn_sched_barrier(0)
; template <class Epi, class Sched, bool ALIGN_EPI = false, bool SP2 = false, bool RS = false, bool BPRE = false>
; __device__ __forceinline__ void gemm_phase(PG8_LAS unsigned char* lds, const Gemm g, const Sched& S, const Epi& E, const float* rs_ss = nullptr, PG8_LAS float* rs_tab = nullptr) {
;     ...
;             PG8_LDA(At, 0, 1); PG8_STAGE(PG8_SB(0, 0), b2, voffB); PG8_STAGE(PG8_SB(0, 1), b2 + hstep, voffB); PG8_STAGE(PG8_SA(0, 0), a2, voffA);
;             PG8_WAIT_V(8); PG8_WAIT_L(0); PG8_BAR; PG8_MMA(1, 0, At, B0); PG8_MMA(1, 1, At, B1); PG8_BAR; PG8_SCHED;
;             PG8_LDB(B0, 1, 0); PG8_LDB(B1, 1, 1); PG8_SCHED; PG8_LDA(At, 1, 0); PG8_STAGE(PG8_SA(0, 1), a2 + hstep, voffA);
;             PG8_WAIT_V(8); PG8_WAIT_L(0); PG8_BAR; PG8_MMA(0, 0, At, B0); PG8_MMA(0, 1, At, B1); PG8_BAR; PG8_SCHED;
	s_setprio 1
	s_waitcnt lgkmcnt(0)
	v_mfma_f32_16x16x32_bf16 v[62:65], v[130:133], v[186:189], 0
	v_mfma_f32_16x16x32_bf16 v[62:65], v[134:137], v[190:193], v[62:65]
	v_mfma_f32_16x16x32_bf16 v[58:61], v[156:159], v[190:193], 0
	v_mfma_f32_16x16x32_bf16 v[58:61], v[152:155], v[186:189], v[58:61]
	v_mfma_f32_16x16x32_bf16 v[42:45], v[152:155], v[194:197], 0
	v_mfma_f32_16x16x32_bf16 v[42:45], v[156:159], v[198:201], v[42:45]
	v_mfma_f32_16x16x32_bf16 v[46:49], v[134:137], v[198:201], 0
	v_mfma_f32_16x16x32_bf16 v[46:49], v[130:133], v[194:197], v[46:49]
	v_mfma_f32_16x16x32_bf16 v[30:33], v[130:133], v[202:205], 0
	v_mfma_f32_16x16x32_bf16 v[30:33], v[134:137], v[206:209], v[30:33]
	v_mfma_f32_16x16x32_bf16 v[26:29], v[156:159], v[206:209], 0
	v_mfma_f32_16x16x32_bf16 v[26:29], v[152:155], v[202:205], v[26:29]
	v_mfma_f32_16x16x32_bf16 v[10:13], v[152:155], v[210:213], 0
	v_mfma_f32_16x16x32_bf16 v[10:13], v[156:159], v[214:217], v[10:13]
	v_mfma_f32_16x16x32_bf16 v[14:17], v[134:137], v[214:217], 0
	v_mfma_f32_16x16x32_bf16 v[14:17], v[130:133], v[210:213], v[14:17]
	s_setprio 0
	s_setprio 1
	v_mfma_f32_16x16x32_bf16 v[54:57], v[166:169], v[186:189], 0
	v_mfma_f32_16x16x32_bf16 v[54:57], v[170:173], v[190:193], v[54:57]
	v_mfma_f32_16x16x32_bf16 v[50:53], v[182:185], v[190:193], 0
	v_mfma_f32_16x16x32_bf16 v[50:53], v[174:177], v[186:189], v[50:53]
	v_mfma_f32_16x16x32_bf16 v[34:37], v[174:177], v[194:197], 0
	v_mfma_f32_16x16x32_bf16 v[34:37], v[182:185], v[198:201], v[34:37]
	v_mfma_f32_16x16x32_bf16 v[38:41], v[170:173], v[198:201], 0
	v_mfma_f32_16x16x32_bf16 v[38:41], v[166:169], v[194:197], v[38:41]
	v_mfma_f32_16x16x32_bf16 v[22:25], v[166:169], v[202:205], 0
	v_mfma_f32_16x16x32_bf16 v[22:25], v[170:173], v[206:209], v[22:25]
	v_mfma_f32_16x16x32_bf16 v[18:21], v[182:185], v[206:209], 0
	v_mfma_f32_16x16x32_bf16 v[18:21], v[174:177], v[202:205], v[18:21]
	v_mfma_f32_16x16x32_bf16 v[2:5], v[174:177], v[210:213], 0
	v_mfma_f32_16x16x32_bf16 v[2:5], v[182:185], v[214:217], v[2:5]
	v_mfma_f32_16x16x32_bf16 v[6:9], v[170:173], v[214:217], 0
	v_mfma_f32_16x16x32_bf16 v[6:9], v[166:169], v[210:213], v[6:9]
	s_setprio 0
	s_barrier
	s_add_i32 s90, 0, 0x18000
	v_add_u32_e32 v143, s90, v160
	s_add_i32 s91, 0, 0x1c000
	ds_read_b128 v[130:133], v143
	ds_read_b128 v[134:137], v143 offset:1024
	ds_read_b128 v[152:155], v143 offset:2048
	ds_read_b128 v[156:159], v143 offset:3072
	v_add_u32_e32 v143, s91, v160
	ds_read_b128 v[166:169], v143
	ds_read_b128 v[170:173], v143 offset:1024
	ds_read_b128 v[174:177], v143 offset:2048
	ds_read_b128 v[182:185], v143 offset:3072
	s_add_u32 s70, s70, 0x80000
	s_addc_u32 s71, s71, 0
	s_mov_b32 m0, s74
	v_lshl_add_u64 v[178:179], s[70:71], 0, v[138:139]
	ds_read_b128 v[186:189], v163 offset:32768
	ds_read_b128 v[190:193], v163 offset:33792
	ds_read_b128 v[194:197], v163 offset:34816
	ds_read_b128 v[198:201], v163 offset:35840
	ds_read_b128 v[202:205], v163 offset:36864
	ds_read_b128 v[206:209], v163 offset:37888
	ds_read_b128 v[210:213], v163 offset:38912
	ds_read_b128 v[214:217], v163 offset:39936
	global_load_lds_dwordx4 v[178:179], off
	v_lshl_add_u64 v[178:179], s[70:71], 0, v[140:141]
	s_mov_b32 m0, s75
	s_nop 0
	global_load_lds_dwordx4 v[178:179], off
	s_waitcnt vmcnt(8)
	s_waitcnt lgkmcnt(0)
	s_barrier
	s_setprio 1
	s_waitcnt lgkmcnt(0)
	v_mfma_f32_16x16x32_bf16 v[126:129], v[130:133], v[186:189], v[126:129]
	v_mfma_f32_16x16x32_bf16 v[126:129], v[134:137], v[190:193], v[126:129]
	v_mfma_f32_16x16x32_bf16 v[122:125], v[156:159], v[190:193], v[122:125]
	v_mfma_f32_16x16x32_bf16 v[122:125], v[152:155], v[186:189], v[122:125]
	v_mfma_f32_16x16x32_bf16 v[106:109], v[152:155], v[194:197], v[106:109]
	v_mfma_f32_16x16x32_bf16 v[106:109], v[156:159], v[198:201], v[106:109]
	v_mfma_f32_16x16x32_bf16 v[110:113], v[134:137], v[198:201], v[110:113]
	v_mfma_f32_16x16x32_bf16 v[110:113], v[130:133], v[194:197], v[110:113]
	v_mfma_f32_16x16x32_bf16 v[94:97], v[130:133], v[202:205], v[94:97]
	v_mfma_f32_16x16x32_bf16 v[94:97], v[134:137], v[206:209], v[94:97]
	v_mfma_f32_16x16x32_bf16 v[90:93], v[156:159], v[206:209], v[90:93]
	v_mfma_f32_16x16x32_bf16 v[90:93], v[152:155], v[202:205], v[90:93]
	v_mfma_f32_16x16x32_bf16 v[74:77], v[152:155], v[210:213], v[74:77]
	v_mfma_f32_16x16x32_bf16 v[74:77], v[156:159], v[214:217], v[74:77]
	v_mfma_f32_16x16x32_bf16 v[78:81], v[134:137], v[214:217], v[78:81]
	v_mfma_f32_16x16x32_bf16 v[78:81], v[130:133], v[210:213], v[78:81]
	s_setprio 0
	s_setprio 1
	v_mfma_f32_16x16x32_bf16 v[118:121], v[166:169], v[186:189], v[118:121]
	v_mfma_f32_16x16x32_bf16 v[118:121], v[170:173], v[190:193], v[118:121]
	v_mfma_f32_16x16x32_bf16 v[114:117], v[182:185], v[190:193], v[114:117]
	v_mfma_f32_16x16x32_bf16 v[114:117], v[174:177], v[186:189], v[114:117]
	v_mfma_f32_16x16x32_bf16 v[98:101], v[174:177], v[194:197], v[98:101]
	v_mfma_f32_16x16x32_bf16 v[98:101], v[182:185], v[198:201], v[98:101]
	v_mfma_f32_16x16x32_bf16 v[102:105], v[170:173], v[198:201], v[102:105]
	v_mfma_f32_16x16x32_bf16 v[102:105], v[166:169], v[194:197], v[102:105]
	v_mfma_f32_16x16x32_bf16 v[86:89], v[166:169], v[202:205], v[86:89]
	v_mfma_f32_16x16x32_bf16 v[86:89], v[170:173], v[206:209], v[86:89]
	v_mfma_f32_16x16x32_bf16 v[82:85], v[182:185], v[206:209], v[82:85]
	v_mfma_f32_16x16x32_bf16 v[82:85], v[174:177], v[202:205], v[82:85]
	v_mfma_f32_16x16x32_bf16 v[66:69], v[174:177], v[210:213], v[66:69]
	v_mfma_f32_16x16x32_bf16 v[66:69], v[182:185], v[214:217], v[66:69]
	v_mfma_f32_16x16x32_bf16 v[70:73], v[170:173], v[214:217], v[70:73]
	v_mfma_f32_16x16x32_bf16 v[70:73], v[166:169], v[210:213], v[70:73]
	s_setprio 0
	s_barrier
; #define PG8_STAGE(bufoff, gbase, voff) do { _Pragma("unroll") for (int _i = 0; _i < 2; ++_i) \
;         __builtin_amdgcn_global_load_lds((const unsigned*)((const char*)(gbase) + (voff)[_i]), (PG8_LAS unsigned*)(lds + (bufoff) + ldsw + _i * 8192), 16, 0, 0); } while (0)
; #define PG8_LDA(dst, b, h) do { _Pragma("unroll") for (int m = 0; m < 4; ++m) _Pragma("unroll") for (int k = 0; k < 2; ++k) dst[m][k] = *(const PG8_LAS bf16x8*)(lds + PG8_SA(b, h) + aoff + m * 2048 + k * 1024); } while (0)
; #define PG8_LDB(dst, b, h) do { _Pragma("unroll") for (int n = 0; n < 2; ++n) _Pragma("unroll") for (int k = 0; k < 2; ++k) dst[n][k] = *(const PG8_LAS bf16x8*)(lds + PG8_SB(b, h) + boff + n * 2048 + k * 1024); } while (0)
; #define PG8_WAIT_V(n) asm volatile("s_waitcnt vmcnt(" #n ")" ::: "memory")
; #define PG8_WAIT_L(n) asm volatile("s_waitcnt lgkmcnt(" #n ")" ::: "memory")
; #define PG8_BAR __builtin_amdgcn_s_barrier()
; #define PG8_SCHED __builtin_amdgcn_sched_barrier(0)
; template <class Epi, class Sched, bool ALIGN_EPI = false, bool SP2 = false, bool RS = false, bool BPRE = false>
; __device__ __forceinline__ void gemm_phase(PG8_LAS unsigned char* lds, const Gemm g, const Sched& S, const Epi& E, const float* rs_ss = nullptr, PG8_LAS float* rs_tab = nullptr) {
;     ...
;             PG8_LDB(B0, 0, 0); PG8_LDB(B1, 0, 1); PG8_SCHED; PG8_LDA(At, 0, 0); PG8_STAGE(PG8_SA(1, 1), a1 + hstep, voffA);
;             PG8_WAIT_V(8); PG8_WAIT_L(0); PG8_BAR; PG8_MMA(0, 0, At, B0); PG8_MMA(0, 1, At, B1); PG8_BAR; PG8_SCHED;
;             PG8_LDA(At, 0, 1); PG8_STAGE(PG8_SB(0, 0), b2, voffB); PG8_STAGE(PG8_SB(0, 1), b2 + hstep, voffB); PG8_STAGE(PG8_SA(0, 0), a2, voffA);
;             PG8_WAIT_V(8); PG8_WAIT_L(0); PG8_BAR; PG8_MMA(1, 0, At, B0); PG8_MMA(1, 1, At, B1); PG8_BAR; PG8_SCHED;
;             PG8_LDB(B0, 1, 0); PG8_LDB(B1, 1, 1); PG8_SCHED; PG8_LDA(At, 1, 0); PG8_STAGE(PG8_SA(0, 1), a2 + hstep, voffA);
;             PG8_WAIT_V(8); PG8_WAIT_L(0); PG8_BAR; PG8_MMA(0, 0, At, B0); PG8_MMA(0, 1, At, B1); PG8_BAR; PG8_SCHED;
;             PG8_LDA(At, 1, 1); PG8_STAGE(PG8_SB(1, 0), b3, voffB); PG8_STAGE(PG8_SB(1, 1), b3 + hstep, voffB); PG8_STAGE(PG8_SA(1, 0), a3, voffA);
;             PG8_WAIT_V(8); PG8_WAIT_L(0); PG8_BAR; PG8_MMA(1, 0, At, B0); PG8_MMA(1, 1, At, B1); PG8_BAR; PG8_SCHED;
	s_add_u32 s70, s60, 0x4000
	s_addc_u32 s71, s61, 0
	s_add_i32 s90, s90, s15
	v_lshl_add_u64 v[178:179], s[70:71], 0, v[138:139]
	s_mov_b32 m0, s90
	ds_read_b128 v[186:189], v163 offset:49152
	ds_read_b128 v[190:193], v163 offset:50176
	ds_read_b128 v[194:197], v163 offset:51200
	ds_read_b128 v[198:201], v163 offset:52224
	ds_read_b128 v[202:205], v163 offset:53248
	ds_read_b128 v[206:209], v163 offset:54272
	ds_read_b128 v[210:213], v163 offset:55296
	ds_read_b128 v[214:217], v163 offset:56320
	global_load_lds_dwordx4 v[178:179], off
	s_add_i32 m0, s90, 0x2000
	s_add_u32 s60, s60, 0x84000
	v_lshl_add_u64 v[178:179], s[70:71], 0, v[140:141]
	s_addc_u32 s61, s61, 0
	s_add_i32 s70, s91, s15
	global_load_lds_dwordx4 v[178:179], off
	v_lshl_add_u64 v[178:179], s[60:61], 0, v[138:139]
	s_mov_b32 m0, s70
	s_nop 0
	global_load_lds_dwordx4 v[178:179], off
	v_lshl_add_u64 v[178:179], s[60:61], 0, v[140:141]
	s_add_i32 m0, s70, 0x2000
	s_nop 0
	global_load_lds_dwordx4 v[178:179], off
	v_lshl_add_u64 v[178:179], s[58:59], 0, v[138:139]
	s_mov_b32 m0, s79
	s_nop 0
	global_load_lds_dwordx4 v[178:179], off
	v_lshl_add_u64 v[178:179], s[58:59], 0, v[140:141]
	s_mov_b32 m0, s80
	s_nop 0
	global_load_lds_dwordx4 v[178:179], off
	s_waitcnt vmcnt(8)
	s_waitcnt lgkmcnt(0)
	s_barrier
	s_setprio 1
	s_waitcnt lgkmcnt(0)
	v_mfma_f32_16x16x32_bf16 v[62:65], v[130:133], v[186:189], v[62:65]
	v_mfma_f32_16x16x32_bf16 v[62:65], v[134:137], v[190:193], v[62:65]
	v_mfma_f32_16x16x32_bf16 v[58:61], v[156:159], v[190:193], v[58:61]
	v_mfma_f32_16x16x32_bf16 v[58:61], v[152:155], v[186:189], v[58:61]
	v_mfma_f32_16x16x32_bf16 v[42:45], v[152:155], v[194:197], v[42:45]
	v_mfma_f32_16x16x32_bf16 v[42:45], v[156:159], v[198:201], v[42:45]
	v_mfma_f32_16x16x32_bf16 v[46:49], v[134:137], v[198:201], v[46:49]
	v_mfma_f32_16x16x32_bf16 v[46:49], v[130:133], v[194:197], v[46:49]
	v_mfma_f32_16x16x32_bf16 v[30:33], v[130:133], v[202:205], v[30:33]
	v_mfma_f32_16x16x32_bf16 v[30:33], v[134:137], v[206:209], v[30:33]
	v_mfma_f32_16x16x32_bf16 v[26:29], v[156:159], v[206:209], v[26:29]
	v_mfma_f32_16x16x32_bf16 v[26:29], v[152:155], v[202:205], v[26:29]
	v_mfma_f32_16x16x32_bf16 v[10:13], v[152:155], v[210:213], v[10:13]
	v_mfma_f32_16x16x32_bf16 v[10:13], v[156:159], v[214:217], v[10:13]
	v_mfma_f32_16x16x32_bf16 v[14:17], v[134:137], v[214:217], v[14:17]
	v_mfma_f32_16x16x32_bf16 v[14:17], v[130:133], v[210:213], v[14:17]
	s_setprio 0
	s_setprio 1
	v_mfma_f32_16x16x32_bf16 v[54:57], v[166:169], v[186:189], v[54:57]
	v_mfma_f32_16x16x32_bf16 v[54:57], v[170:173], v[190:193], v[54:57]
	v_mfma_f32_16x16x32_bf16 v[50:53], v[182:185], v[190:193], v[50:53]
	v_mfma_f32_16x16x32_bf16 v[50:53], v[174:177], v[186:189], v[50:53]
	v_mfma_f32_16x16x32_bf16 v[34:37], v[174:177], v[194:197], v[34:37]
	v_mfma_f32_16x16x32_bf16 v[34:37], v[182:185], v[198:201], v[34:37]
	v_mfma_f32_16x16x32_bf16 v[38:41], v[170:173], v[198:201], v[38:41]
	v_mfma_f32_16x16x32_bf16 v[38:41], v[166:169], v[194:197], v[38:41]
	v_mfma_f32_16x16x32_bf16 v[22:25], v[166:169], v[202:205], v[22:25]
	v_mfma_f32_16x16x32_bf16 v[22:25], v[170:173], v[206:209], v[22:25]
	v_mfma_f32_16x16x32_bf16 v[18:21], v[182:185], v[206:209], v[18:21]
	v_mfma_f32_16x16x32_bf16 v[18:21], v[174:177], v[202:205], v[18:21]
	v_mfma_f32_16x16x32_bf16 v[2:5], v[174:177], v[210:213], v[2:5]
	v_mfma_f32_16x16x32_bf16 v[2:5], v[182:185], v[214:217], v[2:5]
	v_mfma_f32_16x16x32_bf16 v[6:9], v[170:173], v[214:217], v[6:9]
	v_mfma_f32_16x16x32_bf16 v[6:9], v[166:169], v[210:213], v[6:9]
	s_setprio 0
	s_barrier
	s_add_i32 s89, s89, 2
	s_add_u32 s56, s56, 0x8000
	s_addc_u32 s57, s57, 0
	s_add_u32 s87, s87, 0x8000
	s_addc_u32 s88, s88, 0
.LBB0_196:
	ds_read_b128 v[130:133], v161
	ds_read_b128 v[134:137], v161 offset:1024
	ds_read_b128 v[152:155], v161 offset:2048
	ds_read_b128 v[156:159], v161 offset:3072
	ds_read_b128 v[166:169], v162
	ds_read_b128 v[170:173], v162 offset:1024
	ds_read_b128 v[174:177], v162 offset:2048
	ds_read_b128 v[182:185], v162 offset:3072
	s_add_u32 s58, s56, 0xfff84000
	s_addc_u32 s59, s57, -1
	s_cmp_eq_u32 s89, 28
	s_cselect_b32 s70, s19, s58
	s_cselect_b32 s71, s5, s59
	s_cselect_b32 s60, s47, s87
	s_cselect_b32 s61, s17, s88
	s_add_u32 s58, s70, 0x4000
	s_addc_u32 s59, s71, 0
	v_lshl_add_u64 v[178:179], s[56:57], 0, v[138:139]
	s_add_i32 m0, s72, 0xc000
	ds_read_b128 v[186:189], v163
	ds_read_b128 v[190:193], v163 offset:1024
	ds_read_b128 v[194:197], v163 offset:2048
	ds_read_b128 v[198:201], v163 offset:3072
	ds_read_b128 v[202:205], v163 offset:4096
	ds_read_b128 v[206:209], v163 offset:5120
	ds_read_b128 v[210:213], v163 offset:6144
	ds_read_b128 v[214:217], v163 offset:7168
	global_load_lds_dwordx4 v[178:179], off
	v_lshl_add_u64 v[178:179], s[56:57], 0, v[146:147]
	s_add_i32 m0, s72, 0xe000
	s_nop 0
	global_load_lds_dwordx4 v[178:179], off
	s_waitcnt vmcnt(8)
	s_waitcnt lgkmcnt(0)
	s_barrier
; #define PG8_STAGE(bufoff, gbase, voff) do { _Pragma("unroll") for (int _i = 0; _i < 2; ++_i) \
;         __builtin_amdgcn_global_load_lds((const unsigned*)((const char*)(gbase) + (voff)[_i]), (PG8_LAS unsigned*)(lds + (bufoff) + ldsw + _i * 8192), 16, 0, 0); } while (0)
; #define PG8_LDA(dst, b, h) do { _Pragma("unroll") for (int m = 0; m < 4; ++m) _Pragma("unroll") for (int k = 0; k < 2; ++k) dst[m][k] = *(const PG8_LAS bf16x8*)(lds + PG8_SA(b, h) + aoff + m * 2048 + k * 1024); } while (0)
; #define PG8_MMA(ai, bj, At, Bt) do { __builtin_amdgcn_s_setprio(1); _Pragma("unroll") for (int m = 0; m < 4; ++m) _Pragma("unroll") for (int n = 0; n < 2; ++n) _Pragma("unroll") for (int k = 0; k < 2; ++k) \
;         acc[ai][bj][m][n] = __builtin_amdgcn_mfma_f32_16x16x32_bf16(Bt[n][k], At[m][k], acc[ai][bj][m][n], 0, 0, 0); __builtin_amdgcn_s_setprio(0); } while (0)
; #define PG8_WAIT_V(n) asm volatile("s_waitcnt vmcnt(" #n ")" ::: "memory")
; #define PG8_WAIT_L(n) asm volatile("s_waitcnt lgkmcnt(" #n ")" ::: "memory")
; #define PG8_BAR __builtin_amdgcn_s_barrier()
; #define PG8_SCHED __builtin_amdgcn_sched_barrier(0)
; template <class Epi, class Sched, bool ALIGN_EPI = false, bool SP2 = false, bool RS = false, bool BPRE = false>
; __device__ __forceinline__ void gemm_phase(PG8_LAS unsigned char* lds, const Gemm g, const Sched& S, const Epi& E, const float* rs_ss = nullptr, PG8_LAS float* rs_tab = nullptr) {
;     ...
;             PG8_WAIT_V(8); PG8_WAIT_L(0); PG8_BAR; PG8_MMA(0, 0, At, B0); PG8_MMA(0, 1, At, B1); PG8_BAR; PG8_SCHED;
;             PG8_LDA(At, 0, 1); PG8_STAGE(PG8_SB(0, 0), b2, voffB); PG8_STAGE(PG8_SB(0, 1), b2 + hstep, voffB); PG8_STAGE(PG8_SA(0, 0), a2, voffA);
;             PG8_WAIT_V(8); PG8_WAIT_L(0); PG8_BAR; PG8_MMA(1, 0, At, B0); PG8_MMA(1, 1, At, B1); PG8_BAR; PG8_SCHED;
	s_setprio 1
	s_waitcnt lgkmcnt(0)
	v_mfma_f32_16x16x32_bf16 v[126:129], v[130:133], v[186:189], v[126:129]
	v_mfma_f32_16x16x32_bf16 v[126:129], v[134:137], v[190:193], v[126:129]
	v_mfma_f32_16x16x32_bf16 v[122:125], v[156:159], v[190:193], v[122:125]
	v_mfma_f32_16x16x32_bf16 v[122:125], v[152:155], v[186:189], v[122:125]
	v_mfma_f32_16x16x32_bf16 v[106:109], v[152:155], v[194:197], v[106:109]
	v_mfma_f32_16x16x32_bf16 v[106:109], v[156:159], v[198:201], v[106:109]
	v_mfma_f32_16x16x32_bf16 v[110:113], v[134:137], v[198:201], v[110:113]
	v_mfma_f32_16x16x32_bf16 v[110:113], v[130:133], v[194:197], v[110:113]
	v_mfma_f32_16x16x32_bf16 v[94:97], v[130:133], v[202:205], v[94:97]
	v_mfma_f32_16x16x32_bf16 v[94:97], v[134:137], v[206:209], v[94:97]
	v_mfma_f32_16x16x32_bf16 v[90:93], v[156:159], v[206:209], v[90:93]
	v_mfma_f32_16x16x32_bf16 v[90:93], v[152:155], v[202:205], v[90:93]
	v_mfma_f32_16x16x32_bf16 v[74:77], v[152:155], v[210:213], v[74:77]
	v_mfma_f32_16x16x32_bf16 v[74:77], v[156:159], v[214:217], v[74:77]
	v_mfma_f32_16x16x32_bf16 v[78:81], v[134:137], v[214:217], v[78:81]
	v_mfma_f32_16x16x32_bf16 v[78:81], v[130:133], v[210:213], v[78:81]
	s_setprio 0
	s_setprio 1
	v_mfma_f32_16x16x32_bf16 v[118:121], v[166:169], v[186:189], v[118:121]
	v_mfma_f32_16x16x32_bf16 v[118:121], v[170:173], v[190:193], v[118:121]
	v_mfma_f32_16x16x32_bf16 v[114:117], v[182:185], v[190:193], v[114:117]
	v_mfma_f32_16x16x32_bf16 v[114:117], v[174:177], v[186:189], v[114:117]
	v_mfma_f32_16x16x32_bf16 v[98:101], v[174:177], v[194:197], v[98:101]
	v_mfma_f32_16x16x32_bf16 v[98:101], v[182:185], v[198:201], v[98:101]
	v_mfma_f32_16x16x32_bf16 v[102:105], v[170:173], v[198:201], v[102:105]
	v_mfma_f32_16x16x32_bf16 v[102:105], v[166:169], v[194:197], v[102:105]
	v_mfma_f32_16x16x32_bf16 v[86:89], v[166:169], v[202:205], v[86:89]
	v_mfma_f32_16x16x32_bf16 v[86:89], v[170:173], v[206:209], v[86:89]
	v_mfma_f32_16x16x32_bf16 v[82:85], v[182:185], v[206:209], v[82:85]
	v_mfma_f32_16x16x32_bf16 v[82:85], v[174:177], v[202:205], v[82:85]
	v_mfma_f32_16x16x32_bf16 v[66:69], v[174:177], v[210:213], v[66:69]
	v_mfma_f32_16x16x32_bf16 v[66:69], v[182:185], v[214:217], v[66:69]
	v_mfma_f32_16x16x32_bf16 v[70:73], v[170:173], v[214:217], v[70:73]
	v_mfma_f32_16x16x32_bf16 v[70:73], v[166:169], v[210:213], v[70:73]
	s_setprio 0
	s_barrier
	s_add_i32 s90, s83, s15
	v_lshl_add_u64 v[178:179], s[60:61], 0, v[138:139]
	s_mov_b32 m0, s90
	ds_read_b128 v[186:189], v163 offset:16384
	ds_read_b128 v[190:193], v163 offset:17408
	ds_read_b128 v[194:197], v163 offset:18432
	ds_read_b128 v[198:201], v163 offset:19456
	ds_read_b128 v[202:205], v163 offset:20480
	ds_read_b128 v[206:209], v163 offset:21504
	ds_read_b128 v[210:213], v163 offset:22528
	ds_read_b128 v[214:217], v163 offset:23552
	global_load_lds_dwordx4 v[178:179], off
	s_add_i32 m0, s90, 0x2000
	s_add_u32 s90, s60, 0x80000
	v_lshl_add_u64 v[178:179], s[60:61], 0, v[140:141]
	s_addc_u32 s91, s61, 0
	s_add_i32 s92, s86, s15
	global_load_lds_dwordx4 v[178:179], off
	v_lshl_add_u64 v[178:179], s[90:91], 0, v[138:139]
	s_mov_b32 m0, s92
	s_nop 0
	global_load_lds_dwordx4 v[178:179], off
	v_lshl_add_u64 v[178:179], s[90:91], 0, v[140:141]
	s_add_i32 m0, s92, 0x2000
	s_nop 0
	global_load_lds_dwordx4 v[178:179], off
	v_lshl_add_u64 v[178:179], s[70:71], 0, v[138:139]
	s_mov_b32 m0, s72
	s_nop 0
	global_load_lds_dwordx4 v[178:179], off
	v_lshl_add_u64 v[178:179], s[70:71], 0, v[140:141]
	s_mov_b32 m0, s73
	s_nop 0
	global_load_lds_dwordx4 v[178:179], off
	s_waitcnt vmcnt(8)
	s_waitcnt lgkmcnt(0)
	s_barrier
	s_setprio 1
	s_waitcnt lgkmcnt(0)
	v_mfma_f32_16x16x32_bf16 v[62:65], v[130:133], v[186:189], v[62:65]
	v_mfma_f32_16x16x32_bf16 v[62:65], v[134:137], v[190:193], v[62:65]
	v_mfma_f32_16x16x32_bf16 v[58:61], v[156:159], v[190:193], v[58:61]
	v_mfma_f32_16x16x32_bf16 v[58:61], v[152:155], v[186:189], v[58:61]
	v_mfma_f32_16x16x32_bf16 v[42:45], v[152:155], v[194:197], v[42:45]
	v_mfma_f32_16x16x32_bf16 v[42:45], v[156:159], v[198:201], v[42:45]
	v_mfma_f32_16x16x32_bf16 v[46:49], v[134:137], v[198:201], v[46:49]
	v_mfma_f32_16x16x32_bf16 v[46:49], v[130:133], v[194:197], v[46:49]
	v_mfma_f32_16x16x32_bf16 v[30:33], v[130:133], v[202:205], v[30:33]
	v_mfma_f32_16x16x32_bf16 v[30:33], v[134:137], v[206:209], v[30:33]
	v_mfma_f32_16x16x32_bf16 v[26:29], v[156:159], v[206:209], v[26:29]
	v_mfma_f32_16x16x32_bf16 v[26:29], v[152:155], v[202:205], v[26:29]
	v_mfma_f32_16x16x32_bf16 v[10:13], v[152:155], v[210:213], v[10:13]
	v_mfma_f32_16x16x32_bf16 v[10:13], v[156:159], v[214:217], v[10:13]
	v_mfma_f32_16x16x32_bf16 v[14:17], v[134:137], v[214:217], v[14:17]
	v_mfma_f32_16x16x32_bf16 v[14:17], v[130:133], v[210:213], v[14:17]
	s_setprio 0
	s_setprio 1
	v_mfma_f32_16x16x32_bf16 v[54:57], v[166:169], v[186:189], v[54:57]
	v_mfma_f32_16x16x32_bf16 v[54:57], v[170:173], v[190:193], v[54:57]
	v_mfma_f32_16x16x32_bf16 v[50:53], v[182:185], v[190:193], v[50:53]
	v_mfma_f32_16x16x32_bf16 v[50:53], v[174:177], v[186:189], v[50:53]
	v_mfma_f32_16x16x32_bf16 v[34:37], v[174:177], v[194:197], v[34:37]
	v_mfma_f32_16x16x32_bf16 v[34:37], v[182:185], v[198:201], v[34:37]
	v_mfma_f32_16x16x32_bf16 v[38:41], v[170:173], v[198:201], v[38:41]
	v_mfma_f32_16x16x32_bf16 v[38:41], v[166:169], v[194:197], v[38:41]
	v_mfma_f32_16x16x32_bf16 v[22:25], v[166:169], v[202:205], v[22:25]
	v_mfma_f32_16x16x32_bf16 v[22:25], v[170:173], v[206:209], v[22:25]
	v_mfma_f32_16x16x32_bf16 v[18:21], v[182:185], v[206:209], v[18:21]
	v_mfma_f32_16x16x32_bf16 v[18:21], v[174:177], v[202:205], v[18:21]
	v_mfma_f32_16x16x32_bf16 v[2:5], v[174:177], v[210:213], v[2:5]
	v_mfma_f32_16x16x32_bf16 v[2:5], v[182:185], v[214:217], v[2:5]
	v_mfma_f32_16x16x32_bf16 v[6:9], v[170:173], v[214:217], v[6:9]
	v_mfma_f32_16x16x32_bf16 v[6:9], v[166:169], v[210:213], v[6:9]
	s_setprio 0
	s_barrier
; #define PG8_STAGE(bufoff, gbase, voff) do { _Pragma("unroll") for (int _i = 0; _i < 2; ++_i) \
;         __builtin_amdgcn_global_load_lds((const unsigned*)((const char*)(gbase) + (voff)[_i]), (PG8_LAS unsigned*)(lds + (bufoff) + ldsw + _i * 8192), 16, 0, 0); } while (0)
; #define PG8_LDA(dst, b, h) do { _Pragma("unroll") for (int m = 0; m < 4; ++m) _Pragma("unroll") for (int k = 0; k < 2; ++k) dst[m][k] = *(const PG8_LAS bf16x8*)(lds + PG8_SA(b, h) + aoff + m * 2048 + k * 1024); } while (0)
; #define PG8_LDB(dst, b, h) do { _Pragma("unroll") for (int n = 0; n < 2; ++n) _Pragma("unroll") for (int k = 0; k < 2; ++k) dst[n][k] = *(const PG8_LAS bf16x8*)(lds + PG8_SB(b, h) + boff + n * 2048 + k * 1024); } while (0)
; #define PG8_MMA(ai, bj, At, Bt) do { __builtin_amdgcn_s_setprio(1); _Pragma("unroll") for (int m = 0; m < 4; ++m) _Pragma("unroll") for (int n = 0; n < 2; ++n) _Pragma("unroll") for (int k = 0; k < 2; ++k) \
;         acc[ai][bj][m][n] = __builtin_amdgcn_mfma_f32_16x16x32_bf16(Bt[n][k], At[m][k], acc[ai][bj][m][n], 0, 0, 0); __builtin_amdgcn_s_setprio(0); } while (0)
; #define PG8_WAIT_V(n) asm volatile("s_waitcnt vmcnt(" #n ")" ::: "memory")
; #define PG8_WAIT_L(n) asm volatile("s_waitcnt lgkmcnt(" #n ")" ::: "memory")
; #define PG8_BAR __builtin_amdgcn_s_barrier()
; #define PG8_SCHED __builtin_amdgcn_sched_barrier(0)
; template <class Epi, class Sched, bool ALIGN_EPI = false, bool SP2 = false, bool RS = false, bool BPRE = false>
; __device__ __forceinline__ void gemm_phase(PG8_LAS unsigned char* lds, const Gemm g, const Sched& S, const Epi& E, const float* rs_ss = nullptr, PG8_LAS float* rs_tab = nullptr) {
;     ...
;             PG8_LDB(B0, 1, 0); PG8_LDB(B1, 1, 1); PG8_SCHED; PG8_LDA(At, 1, 0); PG8_STAGE(PG8_SA(0, 1), a2 + hstep, voffA);
;             PG8_WAIT_V(8); PG8_WAIT_L(0); PG8_BAR; PG8_MMA(0, 0, At, B0); PG8_MMA(0, 1, At, B1); PG8_BAR; PG8_SCHED;
	s_add_i32 s90, 0, 0x18000
	v_add_u32_e32 v143, s90, v160
	s_add_i32 s91, 0, 0x1c000
	ds_read_b128 v[130:133], v143
	ds_read_b128 v[134:137], v143 offset:1024
	ds_read_b128 v[152:155], v143 offset:2048
	ds_read_b128 v[156:159], v143 offset:3072
	v_add_u32_e32 v143, s91, v160
	ds_read_b128 v[166:169], v143
	ds_read_b128 v[170:173], v143 offset:1024
	ds_read_b128 v[174:177], v143 offset:2048
	ds_read_b128 v[182:185], v143 offset:3072
	s_add_u32 s70, s70, 0x80000
	s_addc_u32 s71, s71, 0
	s_mov_b32 m0, s74
	v_lshl_add_u64 v[178:179], s[70:71], 0, v[138:139]
	ds_read_b128 v[186:189], v163 offset:32768
	ds_read_b128 v[190:193], v163 offset:33792
	ds_read_b128 v[194:197], v163 offset:34816
	ds_read_b128 v[198:201], v163 offset:35840
	ds_read_b128 v[202:205], v163 offset:36864
	ds_read_b128 v[206:209], v163 offset:37888
	ds_read_b128 v[210:213], v163 offset:38912
	ds_read_b128 v[214:217], v163 offset:39936
	global_load_lds_dwordx4 v[178:179], off
	v_lshl_add_u64 v[178:179], s[70:71], 0, v[140:141]
	s_mov_b32 m0, s75
	s_nop 0
	global_load_lds_dwordx4 v[178:179], off
	s_waitcnt vmcnt(8)
	s_waitcnt lgkmcnt(0)
	s_barrier
	s_setprio 1
	s_waitcnt lgkmcnt(0)
	v_mfma_f32_16x16x32_bf16 v[126:129], v[130:133], v[186:189], v[126:129]
	v_mfma_f32_16x16x32_bf16 v[126:129], v[134:137], v[190:193], v[126:129]
	v_mfma_f32_16x16x32_bf16 v[122:125], v[156:159], v[190:193], v[122:125]
	v_mfma_f32_16x16x32_bf16 v[122:125], v[152:155], v[186:189], v[122:125]
	v_mfma_f32_16x16x32_bf16 v[106:109], v[152:155], v[194:197], v[106:109]
	v_mfma_f32_16x16x32_bf16 v[106:109], v[156:159], v[198:201], v[106:109]
	v_mfma_f32_16x16x32_bf16 v[110:113], v[134:137], v[198:201], v[110:113]
	v_mfma_f32_16x16x32_bf16 v[110:113], v[130:133], v[194:197], v[110:113]
	v_mfma_f32_16x16x32_bf16 v[94:97], v[130:133], v[202:205], v[94:97]
	v_mfma_f32_16x16x32_bf16 v[94:97], v[134:137], v[206:209], v[94:97]
	v_mfma_f32_16x16x32_bf16 v[90:93], v[156:159], v[206:209], v[90:93]
	v_mfma_f32_16x16x32_bf16 v[90:93], v[152:155], v[202:205], v[90:93]
	v_mfma_f32_16x16x32_bf16 v[74:77], v[152:155], v[210:213], v[74:77]
	v_mfma_f32_16x16x32_bf16 v[74:77], v[156:159], v[214:217], v[74:77]
	v_mfma_f32_16x16x32_bf16 v[78:81], v[134:137], v[214:217], v[78:81]
	v_mfma_f32_16x16x32_bf16 v[78:81], v[130:133], v[210:213], v[78:81]
	s_setprio 0
	s_setprio 1
	v_mfma_f32_16x16x32_bf16 v[118:121], v[166:169], v[186:189], v[118:121]
	v_mfma_f32_16x16x32_bf16 v[118:121], v[170:173], v[190:193], v[118:121]
	v_mfma_f32_16x16x32_bf16 v[114:117], v[182:185], v[190:193], v[114:117]
	v_mfma_f32_16x16x32_bf16 v[114:117], v[174:177], v[186:189], v[114:117]
	v_mfma_f32_16x16x32_bf16 v[98:101], v[174:177], v[194:197], v[98:101]
	v_mfma_f32_16x16x32_bf16 v[98:101], v[182:185], v[198:201], v[98:101]
	v_mfma_f32_16x16x32_bf16 v[102:105], v[170:173], v[198:201], v[102:105]
	v_mfma_f32_16x16x32_bf16 v[102:105], v[166:169], v[194:197], v[102:105]
	v_mfma_f32_16x16x32_bf16 v[86:89], v[166:169], v[202:205], v[86:89]
	v_mfma_f32_16x16x32_bf16 v[86:89], v[170:173], v[206:209], v[86:89]
	v_mfma_f32_16x16x32_bf16 v[82:85], v[182:185], v[206:209], v[82:85]
	v_mfma_f32_16x16x32_bf16 v[82:85], v[174:177], v[202:205], v[82:85]
	v_mfma_f32_16x16x32_bf16 v[66:69], v[174:177], v[210:213], v[66:69]
	v_mfma_f32_16x16x32_bf16 v[66:69], v[182:185], v[214:217], v[66:69]
	v_mfma_f32_16x16x32_bf16 v[70:73], v[170:173], v[214:217], v[70:73]
	v_mfma_f32_16x16x32_bf16 v[70:73], v[166:169], v[210:213], v[70:73]
	s_setprio 0
	s_barrier
; #define PG8_STAGE(bufoff, gbase, voff) do { _Pragma("unroll") for (int _i = 0; _i < 2; ++_i) \
;         __builtin_amdgcn_global_load_lds((const unsigned*)((const char*)(gbase) + (voff)[_i]), (PG8_LAS unsigned*)(lds + (bufoff) + ldsw + _i * 8192), 16, 0, 0); } while (0)
; #define PG8_LDA(dst, b, h) do { _Pragma("unroll") for (int m = 0; m < 4; ++m) _Pragma("unroll") for (int k = 0; k < 2; ++k) dst[m][k] = *(const PG8_LAS bf16x8*)(lds + PG8_SA(b, h) + aoff + m * 2048 + k * 1024); } while (0)
; #define PG8_MMA(ai, bj, At, Bt) do { __builtin_amdgcn_s_setprio(1); _Pragma("unroll") for (int m = 0; m < 4; ++m) _Pragma("unroll") for (int n = 0; n < 2; ++n) _Pragma("unroll") for (int k = 0; k < 2; ++k) \
;         acc[ai][bj][m][n] = __builtin_amdgcn_mfma_f32_16x16x32_bf16(Bt[n][k], At[m][k], acc[ai][bj][m][n], 0, 0, 0); __builtin_amdgcn_s_setprio(0); } while (0)
; #define PG8_WAIT_V(n) asm volatile("s_waitcnt vmcnt(" #n ")" ::: "memory")
; #define PG8_WAIT_L(n) asm volatile("s_waitcnt lgkmcnt(" #n ")" ::: "memory")
; #define PG8_BAR __builtin_amdgcn_s_barrier()
; #define PG8_SCHED __builtin_amdgcn_sched_barrier(0)
; template <class Epi, class Sched, bool ALIGN_EPI = false, bool SP2 = false, bool RS = false, bool BPRE = false>
; __device__ __forceinline__ void gemm_phase(PG8_LAS unsigned char* lds, const Gemm g, const Sched& S, const Epi& E, const float* rs_ss = nullptr, PG8_LAS float* rs_tab = nullptr) {
;     ...
;             PG8_LDA(At, 1, 1); PG8_STAGE(PG8_SB(1, 0), b3, voffB); PG8_STAGE(PG8_SB(1, 1), b3 + hstep, voffB); PG8_STAGE(PG8_SA(1, 0), a3, voffA);
;             PG8_WAIT_V(8); PG8_WAIT_L(0); PG8_BAR; PG8_MMA(1, 0, At, B0); PG8_MMA(1, 1, At, B1); PG8_BAR; PG8_SCHED;
;     ...
;         }
;         if constexpr (ALIGN_EPI) { if (wr == 0) PG8_BAR; }
	s_add_u32 s70, s60, 0x4000
	s_addc_u32 s71, s61, 0
	s_add_i32 s90, s90, s15
	v_lshl_add_u64 v[178:179], s[70:71], 0, v[138:139]
	s_mov_b32 m0, s90
	ds_read_b128 v[186:189], v163 offset:49152
	ds_read_b128 v[190:193], v163 offset:50176
	ds_read_b128 v[194:197], v163 offset:51200
	ds_read_b128 v[198:201], v163 offset:52224
	ds_read_b128 v[202:205], v163 offset:53248
	ds_read_b128 v[206:209], v163 offset:54272
	ds_read_b128 v[210:213], v163 offset:55296
	ds_read_b128 v[214:217], v163 offset:56320
	global_load_lds_dwordx4 v[178:179], off
	s_add_i32 m0, s90, 0x2000
	s_add_u32 s60, s60, 0x84000
	v_lshl_add_u64 v[178:179], s[70:71], 0, v[140:141]
	s_addc_u32 s61, s61, 0
	s_add_i32 s70, s91, s15
	global_load_lds_dwordx4 v[178:179], off
	v_lshl_add_u64 v[178:179], s[60:61], 0, v[138:139]
	s_mov_b32 m0, s70
	s_nop 0
	global_load_lds_dwordx4 v[178:179], off
	v_lshl_add_u64 v[178:179], s[60:61], 0, v[140:141]
	s_add_i32 m0, s70, 0x2000
	s_nop 0
	global_load_lds_dwordx4 v[178:179], off
	v_lshl_add_u64 v[178:179], s[58:59], 0, v[138:139]
	s_mov_b32 m0, s79
	s_nop 0
	global_load_lds_dwordx4 v[178:179], off
	v_lshl_add_u64 v[178:179], s[58:59], 0, v[140:141]
	s_mov_b32 m0, s80
	s_nop 0
	global_load_lds_dwordx4 v[178:179], off
	s_waitcnt vmcnt(8)
	s_waitcnt lgkmcnt(0)
	s_barrier
	s_setprio 1
	s_waitcnt lgkmcnt(0)
	v_mfma_f32_16x16x32_bf16 v[62:65], v[130:133], v[186:189], v[62:65]
	v_mfma_f32_16x16x32_bf16 v[62:65], v[134:137], v[190:193], v[62:65]
	v_mfma_f32_16x16x32_bf16 v[58:61], v[156:159], v[190:193], v[58:61]
	v_mfma_f32_16x16x32_bf16 v[58:61], v[152:155], v[186:189], v[58:61]
	v_mfma_f32_16x16x32_bf16 v[42:45], v[152:155], v[194:197], v[42:45]
	v_mfma_f32_16x16x32_bf16 v[42:45], v[156:159], v[198:201], v[42:45]
	v_mfma_f32_16x16x32_bf16 v[46:49], v[134:137], v[198:201], v[46:49]
	v_mfma_f32_16x16x32_bf16 v[46:49], v[130:133], v[194:197], v[46:49]
	v_mfma_f32_16x16x32_bf16 v[30:33], v[130:133], v[202:205], v[30:33]
	v_mfma_f32_16x16x32_bf16 v[30:33], v[134:137], v[206:209], v[30:33]
	v_mfma_f32_16x16x32_bf16 v[26:29], v[156:159], v[206:209], v[26:29]
	v_mfma_f32_16x16x32_bf16 v[26:29], v[152:155], v[202:205], v[26:29]
	v_mfma_f32_16x16x32_bf16 v[10:13], v[152:155], v[210:213], v[10:13]
	v_mfma_f32_16x16x32_bf16 v[10:13], v[156:159], v[214:217], v[10:13]
	v_mfma_f32_16x16x32_bf16 v[14:17], v[134:137], v[214:217], v[14:17]
	v_mfma_f32_16x16x32_bf16 v[14:17], v[130:133], v[210:213], v[14:17]
	s_setprio 0
	s_setprio 1
	v_mfma_f32_16x16x32_bf16 v[54:57], v[166:169], v[186:189], v[54:57]
	v_mfma_f32_16x16x32_bf16 v[54:57], v[170:173], v[190:193], v[54:57]
	v_mfma_f32_16x16x32_bf16 v[50:53], v[182:185], v[190:193], v[50:53]
	v_mfma_f32_16x16x32_bf16 v[50:53], v[174:177], v[186:189], v[50:53]
	v_mfma_f32_16x16x32_bf16 v[34:37], v[174:177], v[194:197], v[34:37]
	v_mfma_f32_16x16x32_bf16 v[34:37], v[182:185], v[198:201], v[34:37]
	v_mfma_f32_16x16x32_bf16 v[38:41], v[170:173], v[198:201], v[38:41]
	v_mfma_f32_16x16x32_bf16 v[38:41], v[166:169], v[194:197], v[38:41]
	v_mfma_f32_16x16x32_bf16 v[22:25], v[166:169], v[202:205], v[22:25]
	v_mfma_f32_16x16x32_bf16 v[22:25], v[170:173], v[206:209], v[22:25]
	v_mfma_f32_16x16x32_bf16 v[18:21], v[182:185], v[206:209], v[18:21]
	v_mfma_f32_16x16x32_bf16 v[18:21], v[174:177], v[202:205], v[18:21]
	v_mfma_f32_16x16x32_bf16 v[2:5], v[174:177], v[210:213], v[2:5]
	v_mfma_f32_16x16x32_bf16 v[2:5], v[182:185], v[214:217], v[2:5]
	v_mfma_f32_16x16x32_bf16 v[6:9], v[170:173], v[214:217], v[6:9]
	v_mfma_f32_16x16x32_bf16 v[6:9], v[166:169], v[210:213], v[6:9]
	s_setprio 0
	s_barrier
	s_add_i32 s89, s89, 2
	s_add_u32 s56, s56, 0x8000
	s_addc_u32 s57, s57, 0
	s_add_u32 s87, s87, 0x8000
	s_addc_u32 s88, s88, 0
	s_cmp_gt_u32 s89, 29
	s_cbranch_scc0 .LBB0_196
	s_and_b64 vcc, exec, s[12:13]
	s_cbranch_vccz .LBB0_199
	s_barrier
